# S2 epilogue prefetch refined: per-group counted waits (vmcnt 24/20/16/12) and register copies deferred to each group's first use
# baseline (speedup 1.0000x reference)
.LBB0_497:
	s_or_b64 exec, exec, s[4:5]
	v_add_u32_e32 v138, 0x80, v196
	v_ashrrev_i32_e32 v139, 31, v138
	s_waitcnt lgkmcnt(0)
	v_lshlrev_b64 v[64:65], 13, v[138:139]
	v_lshl_add_u64 v[64:65], v[194:195], 0, v[64:65]
	s_waitcnt vmcnt(24)
	v_mov_b64_e32 v[122:123], v[234:235]
	v_mov_b64_e32 v[124:125], v[236:237]
	v_mov_b64_e32 v[126:127], v[238:239]
	v_mov_b64_e32 v[128:129], v[240:241]
	v_mov_b64_e32 v[130:131], v[242:243]
	v_mov_b64_e32 v[132:133], v[244:245]
	v_mov_b64_e32 v[134:135], v[246:247]
	v_mov_b64_e32 v[136:137], v[248:249]
	v_add_u32_e32 v118, 0x90, v196
	v_add_u32_e32 v116, 0xa0, v196
	v_add_u32_e32 v114, 0xb0, v196
	v_ashrrev_i32_e32 v119, 31, v118
	v_ashrrev_i32_e32 v117, 31, v116
	v_ashrrev_i32_e32 v115, 31, v114
	v_lshlrev_b64 v[64:65], 13, v[118:119]
	v_lshlrev_b64 v[66:67], 13, v[116:117]
	v_lshlrev_b64 v[68:69], 13, v[114:115]
	v_lshl_add_u64 v[64:65], v[194:195], 0, v[64:65]
	v_lshl_add_u64 v[66:67], v[194:195], 0, v[66:67]
	v_lshl_add_u64 v[68:69], v[194:195], 0, v[68:69]
	s_nop 0
	s_nop 0
	v_lshlrev_b64 v[138:139], 12, v[138:139]
	v_pk_fma_f32 v[62:63], v[62:63], 0.5, v[124:125] op_sel_hi:[1,0,1]
	v_pk_fma_f32 v[60:61], v[60:61], 0.5, v[122:123] op_sel_hi:[1,0,1]
	v_pk_fma_f32 v[58:59], v[58:59], 0.5, v[128:129] op_sel_hi:[1,0,1]
	v_pk_fma_f32 v[56:57], v[56:57], 0.5, v[126:127] op_sel_hi:[1,0,1]
	v_pk_fma_f32 v[54:55], v[54:55], 0.5, v[132:133] op_sel_hi:[1,0,1]
	v_pk_fma_f32 v[52:53], v[52:53], 0.5, v[130:131] op_sel_hi:[1,0,1]
	v_pk_fma_f32 v[122:123], v[50:51], 0.5, v[136:137] op_sel_hi:[1,0,1]
	v_pk_fma_f32 v[124:125], v[48:49], 0.5, v[134:135] op_sel_hi:[1,0,1]
	v_cvt_pk_bf16_f32 v48, v60, v61
	v_cvt_pk_bf16_f32 v49, v62, v63
	v_cvt_pk_bf16_f32 v50, v56, v57
	v_cvt_pk_bf16_f32 v51, v58, v59
	v_mul_f32_e32 v61, v61, v61
	v_mul_f32_e32 v63, v63, v63
	v_mul_f32_e32 v57, v57, v57
	v_mul_f32_e32 v59, v59, v59
	v_mul_f32_e32 v121, v53, v53
	v_mul_f32_e32 v126, v55, v55
	v_mul_f32_e32 v127, v125, v125
	v_mul_f32_e32 v128, v123, v123
	v_fmac_f32_e32 v61, v60, v60
	v_fmac_f32_e32 v63, v62, v62
	v_fmac_f32_e32 v57, v56, v56
	v_fmac_f32_e32 v59, v58, v58
	v_fmac_f32_e32 v121, v52, v52
	v_fmac_f32_e32 v126, v54, v54
	v_fmac_f32_e32 v127, v124, v124
	v_fmac_f32_e32 v128, v122, v122
	v_add_f32_e32 v56, v61, v63
	v_add_f32_e32 v57, v57, v59
	v_add_f32_e32 v58, v121, v126
	v_add_f32_e32 v59, v127, v128
	v_add_f32_e32 v56, v56, v57
	v_add_f32_e32 v57, v58, v59
	v_add_f32_e32 v58, v56, v57
	ds_bpermute_b32 v59, v212, v58
	v_lshl_add_u64 v[56:57], s[16:17], 0, v[138:139]
	v_lshl_add_u64 v[56:57], v[192:193], 1, v[56:57]
	global_store_dwordx4 v[56:57], v[48:51], off
	s_waitcnt lgkmcnt(0)
	s_nop 0
	v_add_f32_e32 v48, v58, v59
	ds_bpermute_b32 v49, v120, v48
	v_cvt_pk_bf16_f32 v50, v52, v53
	v_cvt_pk_bf16_f32 v51, v54, v55
	v_cvt_pk_bf16_f32 v52, v124, v125
	v_cvt_pk_bf16_f32 v53, v122, v123
	global_store_dwordx4 v[56:57], v[50:53], off offset:256
	s_and_saveexec_b64 s[4:5], s[6:7]
	s_nop 0
	s_waitcnt lgkmcnt(0)
	v_add_f32_e32 v48, v48, v49
	global_atomic_add_f32 v[112:113], v48, off offset:512
.LBB0_499:
	s_or_b64 exec, exec, s[4:5]
	s_waitcnt vmcnt(20)
	v_mov_b64_e32 v[104:105], v[214:215]
	v_mov_b64_e32 v[106:107], v[216:217]
	v_mov_b64_e32 v[108:109], v[218:219]
	v_mov_b64_e32 v[110:111], v[220:221]
	v_mov_b64_e32 v[96:97], v[222:223]
	v_mov_b64_e32 v[98:99], v[224:225]
	v_mov_b64_e32 v[100:101], v[226:227]
	v_mov_b64_e32 v[102:103], v[228:229]
	v_pk_fma_f32 v[44:45], v[44:45], 0.5, v[108:109] op_sel_hi:[1,0,1]
	v_pk_fma_f32 v[46:47], v[46:47], 0.5, v[110:111] op_sel_hi:[1,0,1]
	v_pk_fma_f32 v[52:53], v[40:41], 0.5, v[104:105] op_sel_hi:[1,0,1]
	v_cvt_pk_bf16_f32 v40, v44, v45
	v_mul_f32_e32 v45, v45, v45
	v_fmac_f32_e32 v45, v44, v44
	v_mul_f32_e32 v44, v47, v47
	v_pk_fma_f32 v[50:51], v[42:43], 0.5, v[106:107] op_sel_hi:[1,0,1]
	v_fmac_f32_e32 v44, v46, v46
	v_cvt_pk_bf16_f32 v41, v46, v47
	v_add_f32_e32 v44, v45, v44
	v_mul_f32_e32 v45, v53, v53
	v_mul_f32_e32 v46, v51, v51
	v_fmac_f32_e32 v45, v52, v52
	v_fmac_f32_e32 v46, v50, v50
	v_pk_fma_f32 v[38:39], v[38:39], 0.5, v[102:103] op_sel_hi:[1,0,1]
	v_pk_fma_f32 v[36:37], v[36:37], 0.5, v[100:101] op_sel_hi:[1,0,1]
	v_add_f32_e32 v45, v45, v46
	v_pk_fma_f32 v[46:47], v[32:33], 0.5, v[96:97] op_sel_hi:[1,0,1]
	v_mul_f32_e32 v32, v37, v37
	v_mul_f32_e32 v33, v39, v39
	v_cvt_pk_bf16_f32 v42, v52, v53
	v_cvt_pk_bf16_f32 v43, v50, v51
	v_add_f32_e32 v50, v44, v45
	v_pk_fma_f32 v[44:45], v[34:35], 0.5, v[98:99] op_sel_hi:[1,0,1]
	v_fmac_f32_e32 v32, v36, v36
	v_fmac_f32_e32 v33, v38, v38
	v_add_f32_e32 v32, v32, v33
	v_mul_f32_e32 v33, v47, v47
	v_mul_f32_e32 v34, v45, v45
	v_fmac_f32_e32 v33, v46, v46
	v_fmac_f32_e32 v34, v44, v44
	v_add_f32_e32 v33, v33, v34
	v_add_f32_e32 v32, v32, v33
	v_add_f32_e32 v35, v50, v32
	ds_bpermute_b32 v50, v212, v35
	s_waitcnt lgkmcnt(0)
	v_lshlrev_b64 v[48:49], 12, v[118:119]
	v_lshl_add_u64 v[32:33], s[16:17], 0, v[48:49]
	v_lshl_add_u64 v[48:49], v[192:193], 1, v[32:33]
	global_store_dwordx4 v[48:49], v[40:43], off
	v_add_f32_e32 v32, v35, v50
	ds_bpermute_b32 v33, v120, v32
	v_cvt_pk_bf16_f32 v34, v36, v37
	v_cvt_pk_bf16_f32 v35, v38, v39
	v_cvt_pk_bf16_f32 v36, v46, v47
	v_cvt_pk_bf16_f32 v37, v44, v45
	global_store_dwordx4 v[48:49], v[34:37], off offset:256
	s_and_saveexec_b64 s[4:5], s[6:7]
	s_nop 0
	s_waitcnt lgkmcnt(0)
	v_add_f32_e32 v32, v32, v33
	global_atomic_add_f32 v[112:113], v32, off offset:576
.LBB0_501:
	s_or_b64 exec, exec, s[4:5]
	s_waitcnt vmcnt(16)
	v_mov_b64_e32 v[88:89], v[160:161]
	v_mov_b64_e32 v[90:91], v[162:163]
	v_mov_b64_e32 v[92:93], v[164:165]
	v_mov_b64_e32 v[94:95], v[166:167]
	v_mov_b64_e32 v[80:81], v[168:169]
	v_mov_b64_e32 v[82:83], v[170:171]
	v_mov_b64_e32 v[84:85], v[172:173]
	v_mov_b64_e32 v[86:87], v[174:175]
	v_pk_fma_f32 v[28:29], v[28:29], 0.5, v[92:93] op_sel_hi:[1,0,1]
	v_pk_fma_f32 v[30:31], v[30:31], 0.5, v[94:95] op_sel_hi:[1,0,1]
	v_pk_fma_f32 v[36:37], v[24:25], 0.5, v[88:89] op_sel_hi:[1,0,1]
	v_cvt_pk_bf16_f32 v24, v28, v29
	v_mul_f32_e32 v29, v29, v29
	v_fmac_f32_e32 v29, v28, v28
	v_mul_f32_e32 v28, v31, v31
	v_pk_fma_f32 v[34:35], v[26:27], 0.5, v[90:91] op_sel_hi:[1,0,1]
	v_fmac_f32_e32 v28, v30, v30
	v_cvt_pk_bf16_f32 v25, v30, v31
	v_add_f32_e32 v28, v29, v28
	v_mul_f32_e32 v29, v37, v37
	v_mul_f32_e32 v30, v35, v35
	v_fmac_f32_e32 v29, v36, v36
	v_fmac_f32_e32 v30, v34, v34
	v_pk_fma_f32 v[22:23], v[22:23], 0.5, v[86:87] op_sel_hi:[1,0,1]
	v_pk_fma_f32 v[20:21], v[20:21], 0.5, v[84:85] op_sel_hi:[1,0,1]
	v_add_f32_e32 v29, v29, v30
	v_pk_fma_f32 v[30:31], v[16:17], 0.5, v[80:81] op_sel_hi:[1,0,1]
	v_mul_f32_e32 v16, v21, v21
	v_mul_f32_e32 v17, v23, v23
	v_cvt_pk_bf16_f32 v26, v36, v37
	v_cvt_pk_bf16_f32 v27, v34, v35
	v_add_f32_e32 v34, v28, v29
	v_pk_fma_f32 v[28:29], v[18:19], 0.5, v[82:83] op_sel_hi:[1,0,1]
	v_fmac_f32_e32 v16, v20, v20
	v_fmac_f32_e32 v17, v22, v22
	v_add_f32_e32 v16, v16, v17
	v_mul_f32_e32 v17, v31, v31
	v_mul_f32_e32 v18, v29, v29
	v_fmac_f32_e32 v17, v30, v30
	v_fmac_f32_e32 v18, v28, v28
	v_add_f32_e32 v17, v17, v18
	v_add_f32_e32 v16, v16, v17
	v_add_f32_e32 v19, v34, v16
	ds_bpermute_b32 v34, v212, v19
	s_waitcnt lgkmcnt(0)
	v_lshlrev_b64 v[32:33], 12, v[116:117]
	v_lshl_add_u64 v[16:17], s[16:17], 0, v[32:33]
	v_lshl_add_u64 v[32:33], v[192:193], 1, v[16:17]
	global_store_dwordx4 v[32:33], v[24:27], off
	v_add_f32_e32 v16, v19, v34
	ds_bpermute_b32 v17, v120, v16
	v_cvt_pk_bf16_f32 v18, v20, v21
	v_cvt_pk_bf16_f32 v19, v22, v23
	v_cvt_pk_bf16_f32 v20, v30, v31
	v_cvt_pk_bf16_f32 v21, v28, v29
	global_store_dwordx4 v[32:33], v[18:21], off offset:256
	s_and_saveexec_b64 s[4:5], s[6:7]
	s_nop 0
	s_waitcnt lgkmcnt(0)
	v_add_f32_e32 v16, v16, v17
	global_atomic_add_f32 v[112:113], v16, off offset:640
.LBB0_503:
	s_or_b64 exec, exec, s[4:5]
	s_waitcnt vmcnt(12)
	v_mov_b64_e32 v[72:73], v[144:145]
	v_mov_b64_e32 v[74:75], v[146:147]
	v_mov_b64_e32 v[76:77], v[148:149]
	v_mov_b64_e32 v[78:79], v[150:151]
	v_mov_b64_e32 v[64:65], v[152:153]
	v_mov_b64_e32 v[66:67], v[154:155]
	v_mov_b64_e32 v[68:69], v[156:157]
	v_mov_b64_e32 v[70:71], v[158:159]
	v_pk_fma_f32 v[12:13], v[12:13], 0.5, v[76:77] op_sel_hi:[1,0,1]
	v_pk_fma_f32 v[14:15], v[14:15], 0.5, v[78:79] op_sel_hi:[1,0,1]
	v_pk_fma_f32 v[20:21], v[8:9], 0.5, v[72:73] op_sel_hi:[1,0,1]
	v_cvt_pk_bf16_f32 v8, v12, v13
	v_mul_f32_e32 v13, v13, v13
	v_fmac_f32_e32 v13, v12, v12
	v_mul_f32_e32 v12, v15, v15
	v_pk_fma_f32 v[18:19], v[10:11], 0.5, v[74:75] op_sel_hi:[1,0,1]
	v_fmac_f32_e32 v12, v14, v14
	v_cvt_pk_bf16_f32 v9, v14, v15
	v_add_f32_e32 v12, v13, v12
	v_mul_f32_e32 v13, v21, v21
	v_mul_f32_e32 v14, v19, v19
	v_fmac_f32_e32 v13, v20, v20
	v_fmac_f32_e32 v14, v18, v18
	v_pk_fma_f32 v[6:7], v[6:7], 0.5, v[70:71] op_sel_hi:[1,0,1]
	v_pk_fma_f32 v[4:5], v[4:5], 0.5, v[68:69] op_sel_hi:[1,0,1]
	v_add_f32_e32 v13, v13, v14
	v_pk_fma_f32 v[14:15], v[0:1], 0.5, v[64:65] op_sel_hi:[1,0,1]
	v_mul_f32_e32 v0, v5, v5
	v_mul_f32_e32 v1, v7, v7
	v_cvt_pk_bf16_f32 v10, v20, v21
	v_cvt_pk_bf16_f32 v11, v18, v19
	v_add_f32_e32 v18, v12, v13
	v_pk_fma_f32 v[12:13], v[2:3], 0.5, v[66:67] op_sel_hi:[1,0,1]
	v_fmac_f32_e32 v0, v4, v4
	v_fmac_f32_e32 v1, v6, v6
	v_add_f32_e32 v0, v0, v1
	v_mul_f32_e32 v1, v15, v15
	v_mul_f32_e32 v2, v13, v13
	v_fmac_f32_e32 v1, v14, v14
	v_fmac_f32_e32 v2, v12, v12
	v_add_f32_e32 v1, v1, v2
	v_add_f32_e32 v0, v0, v1
	v_add_f32_e32 v3, v18, v0
	ds_bpermute_b32 v18, v212, v3
	s_waitcnt lgkmcnt(0)
	v_lshlrev_b64 v[16:17], 12, v[114:115]
	v_lshl_add_u64 v[0:1], s[16:17], 0, v[16:17]
	v_lshl_add_u64 v[16:17], v[192:193], 1, v[0:1]
	global_store_dwordx4 v[16:17], v[8:11], off
	v_add_f32_e32 v0, v3, v18
	ds_bpermute_b32 v1, v120, v0
	v_cvt_pk_bf16_f32 v2, v4, v5
	v_cvt_pk_bf16_f32 v3, v6, v7
	v_cvt_pk_bf16_f32 v4, v14, v15
	v_cvt_pk_bf16_f32 v5, v12, v13
	global_store_dwordx4 v[16:17], v[2:5], off offset:256
	s_and_saveexec_b64 s[4:5], s[6:7]
	s_cbranch_execz .LBB0_505
	s_waitcnt lgkmcnt(0)
	v_add_f32_e32 v0, v0, v1
	global_atomic_add_f32 v[112:113], v0, off offset:704
